# P9 out-proj epilogue: residual loads of each row group batched (4 in flight) instead of load-wait-store serialised
# baseline (speedup 1.0000x reference)
.LBB0_905:
	s_lshl_b32 s1, s0, 8
	v_add_u32_e32 v160, s1, v162
	v_lshl_add_u32 v144, s14, 8, v164
	v_ashrrev_i32_e32 v161, 31, v160
	v_ashrrev_i32_e32 v145, 31, v144
	v_readlane_b32 s36, v235, 13
	v_readlane_b32 s37, v235, 14
	s_nop 2
	v_lshl_add_u64 v[222:223], v[144:145], 2, s[36:37]
	global_load_dwordx4 v[206:209], v[222:223], off
	global_load_dwordx4 v[210:213], v[222:223], off offset:64
	global_load_dwordx4 v[214:217], v[222:223], off offset:512
	global_load_dwordx4 v[218:221], v[222:223], off offset:576
	v_lshlrev_b64 v[128:129], 11, v[160:161]
	v_readlane_b32 s56, v235, 28
	v_lshl_add_u64 v[128:129], v[128:129], 0, v[144:145]
	v_readlane_b32 s57, v235, 29
	v_lshlrev_b64 v[146:147], 2, v[128:129]
	s_mov_b64 s[16:17], s[56:57]
	v_lshl_add_u64 v[148:149], s[16:17], 0, v[146:147]
	global_load_dwordx4 v[184:187], v[148:149], off
	global_load_dwordx4 v[188:191], v[148:149], off offset:64
	global_load_dwordx4 v[192:195], v[148:149], off offset:512
	global_load_dwordx4 v[196:199], v[148:149], off offset:576
	v_lshl_add_u64 v[146:147], s[72:73], 0, v[146:147]
	v_or_b32_e32 v158, 16, v160
	v_ashrrev_i32_e32 v159, 31, v158
	v_or_b32_e32 v156, 32, v160
	v_ashrrev_i32_e32 v157, 31, v156
	v_or_b32_e32 v154, 48, v160
	v_ashrrev_i32_e32 v155, 31, v154
	v_add_u32_e32 v152, 0x80, v160
	v_ashrrev_i32_e32 v153, 31, v152
	v_readlane_b32 s58, v235, 30
	v_readlane_b32 s59, v235, 31
	v_readlane_b32 s60, v235, 32
	v_readlane_b32 s61, v235, 33
	v_readlane_b32 s62, v235, 34
	v_readlane_b32 s63, v235, 35
	v_readlane_b32 s64, v235, 36
	v_readlane_b32 s65, v235, 37
	v_readlane_b32 s66, v235, 38
	v_readlane_b32 s67, v235, 39
	v_readlane_b32 s68, v235, 40
	v_readlane_b32 s69, v235, 41
	v_readlane_b32 s70, v235, 42
	v_readlane_b32 s71, v235, 43
	s_waitcnt vmcnt(3)
	v_pk_add_f32 v[130:131], v[126:127], v[186:187]
	v_pk_add_f32 v[128:129], v[124:125], v[184:185]
	global_store_dwordx4 v[146:147], v[128:131], off
	s_waitcnt vmcnt(3)
	v_pk_add_f32 v[122:123], v[122:123], v[190:191]
	v_pk_add_f32 v[120:121], v[120:121], v[188:189]
	global_store_dwordx4 v[146:147], v[120:123], off offset:64
	s_waitcnt vmcnt(3)
	v_pk_add_f32 v[118:119], v[118:119], v[194:195]
	v_pk_add_f32 v[116:117], v[116:117], v[192:193]
	global_store_dwordx4 v[146:147], v[116:119], off offset:512
	v_lshlrev_b64 v[148:149], 11, v[158:159]
	v_lshl_add_u64 v[148:149], v[148:149], 0, v[144:145]
	v_lshlrev_b64 v[148:149], 2, v[148:149]
	v_lshl_add_u64 v[150:151], s[16:17], 0, v[148:149]
	s_waitcnt vmcnt(3)
	v_pk_add_f32 v[126:127], v[106:107], v[198:199]
	v_pk_add_f32 v[124:125], v[104:105], v[196:197]
	global_store_dwordx4 v[146:147], v[124:127], off offset:576
	global_load_dwordx4 v[236:239], v[150:151], off
	global_load_dwordx4 v[240:243], v[150:151], off offset:64
	global_load_dwordx4 v[244:247], v[150:151], off offset:512
	global_load_dwordx4 v[248:251], v[150:151], off offset:576
	v_lshl_add_u64 v[146:147], s[72:73], 0, v[148:149]
	v_lshlrev_b64 v[148:149], 11, v[156:157]
	v_lshl_add_u64 v[148:149], v[148:149], 0, v[144:145]
	v_lshlrev_b64 v[148:149], 2, v[148:149]
	s_waitcnt vmcnt(3)
	v_pk_add_f32 v[114:115], v[114:115], v[238:239]
	v_pk_add_f32 v[112:113], v[112:113], v[236:237]
	global_store_dwordx4 v[146:147], v[112:115], off
	s_waitcnt vmcnt(3)
	v_pk_add_f32 v[106:107], v[110:111], v[242:243]
	v_pk_add_f32 v[104:105], v[108:109], v[240:241]
	global_store_dwordx4 v[146:147], v[104:107], off offset:64
	s_waitcnt vmcnt(3)
	v_pk_add_f32 v[102:103], v[102:103], v[246:247]
	v_pk_add_f32 v[100:101], v[100:101], v[244:245]
	global_store_dwordx4 v[146:147], v[100:103], off offset:512
	v_lshl_add_u64 v[150:151], s[16:17], 0, v[148:149]
	s_waitcnt vmcnt(3)
	v_pk_add_f32 v[110:111], v[90:91], v[250:251]
	v_pk_add_f32 v[108:109], v[88:89], v[248:249]
	global_store_dwordx4 v[146:147], v[108:111], off offset:576
	global_load_dwordx4 v[184:187], v[150:151], off
	global_load_dwordx4 v[188:191], v[150:151], off offset:64
	global_load_dwordx4 v[192:195], v[150:151], off offset:512
	global_load_dwordx4 v[196:199], v[150:151], off offset:576
	v_lshl_add_u64 v[146:147], s[72:73], 0, v[148:149]
	v_lshlrev_b64 v[148:149], 11, v[154:155]
	v_lshl_add_u64 v[148:149], v[148:149], 0, v[144:145]
	v_lshlrev_b64 v[148:149], 2, v[148:149]
	s_waitcnt vmcnt(3)
	v_pk_add_f32 v[98:99], v[98:99], v[186:187]
	v_pk_add_f32 v[96:97], v[96:97], v[184:185]
	global_store_dwordx4 v[146:147], v[96:99], off
	s_waitcnt vmcnt(3)
	v_pk_add_f32 v[90:91], v[94:95], v[190:191]
	v_pk_add_f32 v[88:89], v[92:93], v[188:189]
	global_store_dwordx4 v[146:147], v[88:91], off offset:64
	s_waitcnt vmcnt(3)
	v_pk_add_f32 v[86:87], v[86:87], v[194:195]
	v_pk_add_f32 v[84:85], v[84:85], v[192:193]
	global_store_dwordx4 v[146:147], v[84:87], off offset:512
	v_lshl_add_u64 v[150:151], s[16:17], 0, v[148:149]
	s_waitcnt vmcnt(3)
	v_pk_add_f32 v[94:95], v[74:75], v[198:199]
	v_pk_add_f32 v[92:93], v[72:73], v[196:197]
	global_store_dwordx4 v[146:147], v[92:95], off offset:576
	global_load_dwordx4 v[236:239], v[150:151], off
	global_load_dwordx4 v[240:243], v[150:151], off offset:64
	global_load_dwordx4 v[244:247], v[150:151], off offset:512
	global_load_dwordx4 v[248:251], v[150:151], off offset:576
	v_lshl_add_u64 v[146:147], s[72:73], 0, v[148:149]
	v_lshlrev_b64 v[148:149], 11, v[152:153]
	v_lshl_add_u64 v[148:149], v[148:149], 0, v[144:145]
	v_lshlrev_b64 v[148:149], 2, v[148:149]
	s_waitcnt vmcnt(3)
	v_pk_add_f32 v[82:83], v[82:83], v[238:239]
	v_pk_add_f32 v[80:81], v[80:81], v[236:237]
	global_store_dwordx4 v[146:147], v[80:83], off
	s_waitcnt vmcnt(3)
	v_pk_add_f32 v[74:75], v[78:79], v[242:243]
	v_pk_add_f32 v[72:73], v[76:77], v[240:241]
	global_store_dwordx4 v[146:147], v[72:75], off offset:64
	s_waitcnt vmcnt(3)
	v_pk_add_f32 v[70:71], v[70:71], v[246:247]
	v_pk_add_f32 v[68:69], v[68:69], v[244:245]
	global_store_dwordx4 v[146:147], v[68:71], off offset:512
	v_lshl_add_u64 v[150:151], s[16:17], 0, v[148:149]
	s_waitcnt vmcnt(3)
	v_pk_add_f32 v[78:79], v[66:67], v[250:251]
	v_pk_add_f32 v[76:77], v[64:65], v[248:249]
	global_store_dwordx4 v[146:147], v[76:79], off offset:576
	global_load_dwordx4 v[184:187], v[150:151], off
	global_load_dwordx4 v[188:191], v[150:151], off offset:64
	global_load_dwordx4 v[192:195], v[150:151], off offset:512
	global_load_dwordx4 v[196:199], v[150:151], off offset:576
	v_lshl_add_u64 v[146:147], s[72:73], 0, v[148:149]
	s_waitcnt vmcnt(3)
	v_pk_add_f32 v[66:67], v[62:63], v[186:187]
	v_pk_add_f32 v[64:65], v[60:61], v[184:185]
	global_store_dwordx4 v[146:147], v[64:67], off
	s_waitcnt vmcnt(3)
	v_pk_add_f32 v[58:59], v[58:59], v[190:191]
	v_pk_add_f32 v[56:57], v[56:57], v[188:189]
	global_store_dwordx4 v[146:147], v[56:59], off offset:64
	s_waitcnt vmcnt(3)
	v_pk_add_f32 v[54:55], v[54:55], v[194:195]
	v_pk_add_f32 v[52:53], v[52:53], v[192:193]
	global_store_dwordx4 v[146:147], v[52:55], off offset:512
	v_add_u32_e32 v150, 0x90, v160
	v_ashrrev_i32_e32 v151, 31, v150
	v_lshlrev_b64 v[148:149], 11, v[150:151]
	v_lshl_add_u64 v[148:149], v[148:149], 0, v[144:145]
	v_lshlrev_b64 v[148:149], 2, v[148:149]
	v_lshl_add_u64 v[174:175], s[16:17], 0, v[148:149]
	s_waitcnt vmcnt(3)
	v_pk_add_f32 v[62:63], v[42:43], v[198:199]
	v_pk_add_f32 v[60:61], v[40:41], v[196:197]
	global_store_dwordx4 v[146:147], v[60:63], off offset:576
	global_load_dwordx4 v[236:239], v[174:175], off
	global_load_dwordx4 v[240:243], v[174:175], off offset:64
	global_load_dwordx4 v[244:247], v[174:175], off offset:512
	global_load_dwordx4 v[248:251], v[174:175], off offset:576
	v_lshl_add_u64 v[146:147], s[72:73], 0, v[148:149]
	v_add_u32_e32 v148, 0xa0, v160
	v_ashrrev_i32_e32 v149, 31, v148
	s_waitcnt vmcnt(3)
	v_pk_add_f32 v[50:51], v[50:51], v[238:239]
	v_pk_add_f32 v[48:49], v[48:49], v[236:237]
	global_store_dwordx4 v[146:147], v[48:51], off
	s_waitcnt vmcnt(3)
	v_pk_add_f32 v[42:43], v[46:47], v[242:243]
	v_pk_add_f32 v[40:41], v[44:45], v[240:241]
	global_store_dwordx4 v[146:147], v[40:43], off offset:64
	s_waitcnt vmcnt(3)
	v_pk_add_f32 v[38:39], v[38:39], v[246:247]
	v_pk_add_f32 v[36:37], v[36:37], v[244:245]
	global_store_dwordx4 v[146:147], v[36:39], off offset:512
	v_lshlrev_b64 v[174:175], 11, v[148:149]
	v_lshl_add_u64 v[174:175], v[174:175], 0, v[144:145]
	v_lshlrev_b64 v[174:175], 2, v[174:175]
	v_lshl_add_u64 v[176:177], s[16:17], 0, v[174:175]
	v_lshl_add_u64 v[174:175], s[72:73], 0, v[174:175]
	s_waitcnt vmcnt(3)
	v_pk_add_f32 v[46:47], v[26:27], v[250:251]
	v_pk_add_f32 v[44:45], v[24:25], v[248:249]
	global_store_dwordx4 v[146:147], v[44:47], off offset:576
	global_load_dwordx4 v[184:187], v[176:177], off
	global_load_dwordx4 v[188:191], v[176:177], off offset:64
	global_load_dwordx4 v[192:195], v[176:177], off offset:512
	global_load_dwordx4 v[196:199], v[176:177], off offset:576
	v_add_u32_e32 v146, 0xb0, v160
	v_ashrrev_i32_e32 v147, 31, v146
	s_waitcnt vmcnt(3)
	v_pk_add_f32 v[34:35], v[34:35], v[186:187]
	v_pk_add_f32 v[32:33], v[32:33], v[184:185]
	global_store_dwordx4 v[174:175], v[32:35], off
	s_waitcnt vmcnt(3)
	v_pk_add_f32 v[26:27], v[30:31], v[190:191]
	v_pk_add_f32 v[24:25], v[28:29], v[188:189]
	global_store_dwordx4 v[174:175], v[24:27], off offset:64
	s_waitcnt vmcnt(3)
	v_pk_add_f32 v[22:23], v[22:23], v[194:195]
	v_pk_add_f32 v[20:21], v[20:21], v[192:193]
	global_store_dwordx4 v[174:175], v[20:23], off offset:512
	v_lshlrev_b64 v[176:177], 11, v[146:147]
	v_lshl_add_u64 v[176:177], v[176:177], 0, v[144:145]
	v_lshlrev_b64 v[176:177], 2, v[176:177]
	v_lshl_add_u64 v[178:179], s[16:17], 0, v[176:177]
	v_lshl_add_u64 v[180:181], s[72:73], 0, v[176:177]
	s_waitcnt vmcnt(3)
	v_pk_add_f32 v[30:31], v[10:11], v[198:199]
	v_pk_add_f32 v[28:29], v[8:9], v[196:197]
	global_store_dwordx4 v[174:175], v[28:31], off offset:576
	global_load_dwordx4 v[236:239], v[178:179], off
	global_load_dwordx4 v[240:243], v[178:179], off offset:64
	global_load_dwordx4 v[244:247], v[178:179], off offset:512
	global_load_dwordx4 v[248:251], v[178:179], off offset:576
	s_waitcnt vmcnt(3)
	v_pk_add_f32 v[18:19], v[18:19], v[238:239]
	v_pk_add_f32 v[16:17], v[16:17], v[236:237]
	global_store_dwordx4 v[180:181], v[16:19], off
	s_waitcnt vmcnt(3)
	v_pk_add_f32 v[10:11], v[14:15], v[242:243]
	v_pk_add_f32 v[8:9], v[12:13], v[240:241]
	global_store_dwordx4 v[180:181], v[8:11], off offset:64
	s_waitcnt vmcnt(3)
	v_pk_add_f32 v[6:7], v[6:7], v[246:247]
	v_pk_add_f32 v[4:5], v[4:5], v[244:245]
	global_store_dwordx4 v[180:181], v[4:7], off offset:512
	v_mul_f32_e32 v14, v129, v129
	v_mul_f32_e32 v15, v131, v131
	v_fmac_f32_e32 v14, v128, v128
	v_fmac_f32_e32 v15, v130, v130
	v_add_f32_e32 v14, v14, v15
	v_mul_f32_e32 v15, v121, v121
	v_mul_f32_e32 v178, v123, v123
	v_fmac_f32_e32 v15, v120, v120
	v_fmac_f32_e32 v178, v122, v122
	v_add_f32_e32 v15, v15, v178
	v_add_f32_e32 v14, v14, v15
	v_mul_f32_e32 v15, v117, v117
	v_mul_f32_e32 v178, v119, v119
	v_fmac_f32_e32 v15, v116, v116
	v_fmac_f32_e32 v178, v118, v118
	v_and_b32_e32 v13, 64, v182
	v_add_f32_e32 v15, v15, v178
	v_xor_b32_e32 v12, 16, v182
	v_add_u32_e32 v13, 64, v13
	v_add_f32_e32 v14, v14, v15
	v_mul_f32_e32 v15, v125, v125
	v_mul_f32_e32 v178, v127, v127
	v_cmp_lt_i32_e32 vcc, v12, v13
	v_fmac_f32_e32 v15, v124, v124
	v_fmac_f32_e32 v178, v126, v126
	v_cndmask_b32_e32 v12, v182, v12, vcc
	v_add_f32_e32 v15, v15, v178
	v_lshlrev_b32_e32 v12, 2, v12
	v_add_f32_e32 v14, v14, v15
	ds_bpermute_b32 v15, v12, v14
	v_xor_b32_e32 v178, 32, v182
	v_cmp_lt_i32_e32 vcc, v178, v13
	s_waitcnt lgkmcnt(0)
	v_add_f32_e32 v14, v14, v15
	v_cndmask_b32_e32 v13, v182, v178, vcc
	v_lshlrev_b32_e32 v13, 2, v13
	ds_bpermute_b32 v15, v13, v14
	s_waitcnt vmcnt(3)
	v_pk_add_f32 v[2:3], v[2:3], v[250:251]
	v_pk_add_f32 v[0:1], v[0:1], v[248:249]
	global_store_dwordx4 v[180:181], v[0:3], off offset:576
	s_and_saveexec_b64 s[2:3], s[6:7]
	s_cbranch_execz .LBB0_907
	s_waitcnt lgkmcnt(0)
	v_add_f32_e32 v14, v14, v15
	ds_write_b32 v173, v14
